# mLSTM scan: the two quad-level shuffle-adds per step via DPP quad_perm instead of ds_bpermute round trips (bit-identical)
# baseline (speedup 1.0000x reference)
.Lmls_pf_skip:
	ds_read_b128 v[52:55], v137 offset:46080
	ds_read_b128 v[56:59], v136
	ds_read_b128 v[60:63], v136 offset:16
	ds_read_b128 v[64:67], v137 offset:46096
	ds_read_b128 v[68:71], v137 offset:46112
	ds_read_b128 v[72:75], v137 offset:46128
	s_waitcnt lgkmcnt(4)
	v_fma_mix_f32 v52, v52, v56, 0 op_sel_hi:[0,1,0]
	v_fma_mix_f32 v52, v53, v56, v52 op_sel:[0,1,0] op_sel_hi:[0,1,0]
	v_fma_mix_f32 v52, v54, v57, v52 op_sel_hi:[0,1,0]
	v_fma_mix_f32 v52, v55, v57, v52 op_sel:[0,1,0] op_sel_hi:[0,1,0]
	s_waitcnt lgkmcnt(2)
	v_fma_mix_f32 v52, v64, v58, v52 op_sel_hi:[0,1,0]
	v_fma_mix_f32 v52, v65, v58, v52 op_sel:[0,1,0] op_sel_hi:[0,1,0]
	v_fma_mix_f32 v52, v66, v59, v52 op_sel_hi:[0,1,0]
	v_fma_mix_f32 v52, v67, v59, v52 op_sel:[0,1,0] op_sel_hi:[0,1,0]
	s_waitcnt lgkmcnt(1)
	v_fma_mix_f32 v52, v68, v60, v52 op_sel_hi:[0,1,0]
	v_fma_mix_f32 v52, v69, v60, v52 op_sel:[0,1,0] op_sel_hi:[0,1,0]
	v_fma_mix_f32 v52, v70, v61, v52 op_sel_hi:[0,1,0]
	v_fma_mix_f32 v52, v71, v61, v52 op_sel:[0,1,0] op_sel_hi:[0,1,0]
	s_waitcnt lgkmcnt(0)
	v_fma_mix_f32 v52, v72, v62, v52 op_sel_hi:[0,1,0]
	v_fma_mix_f32 v52, v73, v62, v52 op_sel:[0,1,0] op_sel_hi:[0,1,0]
	v_fma_mix_f32 v52, v74, v63, v52 op_sel_hi:[0,1,0]
	v_fma_mix_f32 v52, v75, v63, v52 op_sel:[0,1,0] op_sel_hi:[0,1,0]
	s_nop 1
	v_add_f32_dpp v52, v52, v52 quad_perm:[1,0,3,2] row_mask:0xf bank_mask:0xf
	s_nop 1
	v_mov_b32_dpp v53, v52 quad_perm:[2,3,0,1] row_mask:0xf bank_mask:0xf
	s_and_saveexec_b64 s[16:17], s[12:13]
	s_cbranch_execz .LBB0_507
	s_waitcnt lgkmcnt(0)
	v_add_f32_e32 v52, v52, v53
	ds_write_b32 v142, v52 offset:46336
